# past: next-group Q loads issued after first sub-tile; first-group list entries fetched with the count
# speedup vs baseline: 1.0248x; 1.0028x over previous
.LBB0_254:
	s_and_b32 s0, s34, 11
	s_cmp_lg_u32 s0, 0
	s_cselect_b64 s[16:17], -1, 0
	s_cmp_lg_u32 s0, 3
	s_cselect_b64 s[18:19], -1, 0
	s_and_b64 s[16:17], s[16:17], s[18:19]
	s_cmp_lg_u32 s34, 8
	s_cselect_b64 s[18:19], -1, 0
	s_and_b64 s[16:17], s[18:19], s[16:17]
	s_add_i32 s0, s34, -13
	s_cmp_lt_u32 s0, -2
	s_cselect_b64 s[18:19], -1, 0
	s_and_b64 s[16:17], s[18:19], s[16:17]
	s_waitcnt vmcnt(3)
	v_cndmask_b32_e64 v0, 0, 1, s[16:17]
	v_cmp_ne_u32_e32 vcc, v0, v177
	s_cbranch_vccnz .LBB0_253
	s_lshl_b32 s0, s34, 15
	v_lshl_add_u64 v[24:25], v[152:153], 0, s[0:1]
	s_lshl_b32 s0, s34, 9
	v_mov_b32_e32 v133, v117
	v_lshl_add_u64 v[28:29], v[154:155], 0, s[0:1]
	v_lshl_add_u64 v[0:1], v[24:25], 0, v[132:133]
	v_mov_b32_e32 v135, v117
	s_barrier
	global_load_dwordx4 v[0:3], v[0:1], off
	s_waitcnt vmcnt(3)
	v_lshl_add_u64 v[4:5], v[28:29], 0, v[134:135]
	v_mov_b32_e32 v137, v117
	global_load_dwordx4 v[4:7], v[4:5], off
	s_waitcnt vmcnt(3)
	v_lshl_add_u64 v[8:9], v[24:25], 0, v[136:137]
	v_mov_b32_e32 v139, v117
	global_load_dwordx4 v[8:11], v[8:9], off
	s_waitcnt vmcnt(3)
	v_lshl_add_u64 v[12:13], v[28:29], 0, v[138:139]
	v_mov_b32_e32 v141, v117
	global_load_dwordx4 v[12:15], v[12:13], off
	v_lshl_add_u64 v[16:17], v[24:25], 0, v[140:141]
	v_mov_b32_e32 v143, v117
	global_load_dwordx4 v[16:19], v[16:17], off
	v_lshl_add_u64 v[20:21], v[28:29], 0, v[142:143]
	v_mov_b32_e32 v149, v117
	global_load_dwordx4 v[20:23], v[20:21], off
	v_lshl_add_u64 v[24:25], v[24:25], 0, v[148:149]
	v_mov_b32_e32 v151, v117
	global_load_dwordx4 v[24:27], v[24:25], off
	v_lshl_add_u64 v[28:29], v[28:29], 0, v[150:151]
	global_load_dwordx4 v[28:31], v[28:29], off
	s_add_i32 s18, s34, s33
	s_ashr_i32 s19, s18, 31
	s_lshl_b64 s[16:17], s[18:19], 2
	s_add_u32 s16, s46, s16
	s_addc_u32 s17, s47, s17
	s_waitcnt vmcnt(7)
	ds_write_b128 v115, v[0:3]
	s_waitcnt vmcnt(6)
	ds_write_b128 v168, v[4:7]
	s_waitcnt vmcnt(5)
	ds_write_b128 v169, v[8:11]
	s_waitcnt vmcnt(4)
	ds_write_b128 v170, v[12:15]
	s_waitcnt vmcnt(3)
	ds_write_b128 v171, v[16:19]
	s_waitcnt vmcnt(2)
	ds_write_b128 v172, v[20:23]
	s_waitcnt vmcnt(1)
	ds_write_b128 v173, v[24:27]
	s_waitcnt vmcnt(0)
	ds_write_b128 v174, v[28:31]
	s_waitcnt lgkmcnt(0)
	s_barrier
	global_load_dword v133, v117, s[16:17]
	s_lshl_b64 s[18:19], s[18:19], 13
	s_add_u32 s18, s48, s18
	s_addc_u32 s19, s49, s19
	v_lshlrev_b32_e32 v232, 1, v175
	v_lshlrev_b32_e32 v233, 1, v176
	global_load_ushort v230, v232, s[18:19]
	global_load_ushort v231, v233, s[18:19]
	s_waitcnt vmcnt(2)
	v_add_u32_e32 v0, 31, v133
	v_ashrrev_i32_e32 v135, 5, v0
	v_cmp_lt_i32_e32 vcc, v196, v135
	s_and_saveexec_b64 s[16:17], vcc
	s_cbranch_execz .LBB0_252
	v_cmp_lt_i32_e64 s[20:21], v175, v133
	v_cmp_lt_i32_e64 s[24:25], v176, v133
	s_mov_b64 s[22:23], 0
	v_mov_b32_e32 v143, v196
	s_waitcnt vmcnt(1)
	v_mov_b32_e32 v141, v230
	v_and_b32_e32 v137, 0xfff, v230
	s_waitcnt vmcnt(0)
	v_mov_b32_e32 v149, v231
	v_and_b32_e32 v139, 0xfff, v231
	v_lshlrev_b32_e32 v116, 7, v137
	v_lshl_add_u64 v[4:5], v[156:157], 0, v[116:117]
	v_lshlrev_b32_e32 v116, 7, v139
	v_lshl_add_u64 v[12:13], v[156:157], 0, v[116:117]
	global_load_dwordx4 v[0:3], v[4:5], off
	s_nop 0
	global_load_dwordx4 v[4:7], v[4:5], off offset:64
	s_nop 0
	global_load_dwordx4 v[8:11], v[12:13], off
	s_nop 0
	global_load_dwordx4 v[12:15], v[12:13], off offset:64
	s_branch .LBB0_258

.LBB0_258:
	v_mov_b32_e32 v16, v143
	v_add_u32_e32 v143, 8, v16
	v_cmp_lt_i32_e32 vcc, v143, v135
	s_mov_b64 s[28:29], s[20:21]
	v_mov_b32_e32 v161, v141
	v_cndmask_b32_e32 v16, v16, v143, vcc
	v_lshl_or_b32 v18, v16, 5, v146
	v_cmp_lt_i32_e64 s[20:21], v18, v133
	s_mov_b64 s[26:27], s[24:25]
	v_mov_b32_e32 v151, v149
	v_cndmask_b32_e64 v16, 0, v18, s[20:21]
	v_ashrrev_i32_e32 v17, 31, v16
	v_lshl_add_u64 v[16:17], v[16:17], 1, s[18:19]
	global_load_ushort v141, v[16:17], off
	v_or_b32_e32 v16, 16, v18
	v_cmp_lt_i32_e64 s[24:25], v16, v133
	v_mov_b32_e32 v162, v137
	v_mov_b32_e32 v160, v139
	v_cndmask_b32_e64 v16, 0, v16, s[24:25]
	v_ashrrev_i32_e32 v17, 31, v16
	v_lshl_add_u64 v[16:17], v[16:17], 1, s[18:19]
	global_load_ushort v149, v[16:17], off
	s_waitcnt vmcnt(4)
	v_mov_b64_e32 v[46:47], v[6:7]
	s_waitcnt vmcnt(2)
	v_mov_b64_e32 v[34:35], v[14:15]
	v_mov_b64_e32 v[44:45], v[4:5]
	v_mov_b64_e32 v[32:33], v[12:13]
	v_mov_b64_e32 v[38:39], v[10:11]
	v_mov_b64_e32 v[42:43], v[2:3]
	v_mov_b64_e32 v[36:37], v[8:9]
	v_mov_b64_e32 v[40:41], v[0:1]
	v_cmp_ge_i32_e32 vcc, v143, v135
	v_mov_b32_e32 v158, 0
	s_mov_b32 s0, 0
	s_or_b64 s[22:23], vcc, s[22:23]
	v_mov_b32_e32 v166, 0xf149f2ca
	v_mov_b32_e32 v159, v158
	v_mov_b32_e32 v164, 0xf149f2ca
	v_mov_b32_e32 v60, v158
	v_mov_b32_e32 v61, v158
	v_mov_b32_e32 v62, v158
	v_mov_b32_e32 v63, v158
	v_mov_b32_e32 v56, v158
	v_mov_b32_e32 v57, v158
	v_mov_b32_e32 v58, v158
	v_mov_b32_e32 v59, v158
	v_mov_b32_e32 v52, v158
	v_mov_b32_e32 v53, v158
	v_mov_b32_e32 v54, v158
	v_mov_b32_e32 v55, v158
	v_mov_b32_e32 v48, v158
	v_mov_b32_e32 v49, v158
	v_mov_b32_e32 v50, v158
	v_mov_b32_e32 v51, v158
	v_mov_b32_e32 v28, v158
	v_mov_b32_e32 v29, v158
	v_mov_b32_e32 v30, v158
	v_mov_b32_e32 v31, v158
	v_mov_b32_e32 v24, v158
	v_mov_b32_e32 v25, v158
	v_mov_b32_e32 v26, v158
	v_mov_b32_e32 v27, v158
	v_mov_b32_e32 v20, v158
	v_mov_b32_e32 v21, v158
	v_mov_b32_e32 v22, v158
	v_mov_b32_e32 v23, v158
	v_mov_b32_e32 v16, v158
	v_mov_b32_e32 v17, v158
	v_mov_b32_e32 v18, v158
	v_mov_b32_e32 v19, v158
	v_mov_b32_e32 v116, v125
.LBB0_259:
	ds_read_b128 v[64:67], v116
	ds_read_b128 v[72:75], v116 offset:64
	ds_read_b128 v[76:79], v116 offset:2304
	ds_read_b128 v[100:103], v116 offset:2368
	v_mov_b32_e32 v163, v164
	v_add_u32_e32 v164, s0, v121
	s_waitcnt lgkmcnt(1)
	v_mfma_f32_16x16x32_bf16 v[198:201], v[76:79], v[40:43], 0
	v_mov_b32_e32 v165, v166
	v_add_u32_e32 v166, 0x2000, v164
	v_add_u32_e32 v167, 0x4000, v164
	v_mfma_f32_16x16x32_bf16 v[104:107], v[76:79], v[36:39], 0
	ds_read_b128 v[80:83], v116 offset:4608
	ds_read_b128 v[76:79], v116 offset:4672
	s_addk_i32 s0, 0x80
	s_cmpk_eq_i32 s0, 0x200
	v_mfma_f32_16x16x32_bf16 v[68:71], v[64:67], v[40:43], 0
	v_mfma_f32_16x16x32_bf16 v[64:67], v[64:67], v[36:39], 0
	s_waitcnt lgkmcnt(1)
	v_mfma_f32_16x16x32_bf16 v[92:95], v[80:83], v[40:43], 0
	v_mfma_f32_16x16x32_bf16 v[84:87], v[80:83], v[36:39], 0
	ds_read_b128 v[88:91], v116 offset:6912
	ds_read_b128 v[80:83], v116 offset:6976
	v_add_u32_e32 v116, 0x2400, v116
	s_waitcnt lgkmcnt(1)
	v_mfma_f32_16x16x32_bf16 v[96:99], v[88:91], v[40:43], 0
	v_mfma_f32_16x16x32_bf16 v[88:91], v[88:91], v[36:39], 0
	v_mfma_f32_16x16x32_bf16 v[68:71], v[72:75], v[44:47], v[68:71]
	v_mfma_f32_16x16x32_bf16 v[72:75], v[72:75], v[32:35], v[64:67]
	v_mfma_f32_16x16x32_bf16 v[64:67], v[100:103], v[44:47], v[198:201]
	v_mfma_f32_16x16x32_bf16 v[100:103], v[100:103], v[32:35], v[104:107]
	s_nop 2
	ds_read2_b64 v[104:107], v164 offset1:4
	ds_read2_b64 v[198:201], v164 offset0:8 offset1:12
	v_add_u32_e32 v164, 0x6000, v164
	v_mfma_f32_16x16x32_bf16 v[92:95], v[76:79], v[44:47], v[92:95]
	v_mfma_f32_16x16x32_bf16 v[76:79], v[76:79], v[32:35], v[84:87]
	s_nop 2
	ds_read2_b64 v[84:87], v166 offset0:32 offset1:36
	ds_read2_b64 v[202:205], v166 offset0:40 offset1:44
	ds_read2_b64 v[206:209], v167 offset0:64 offset1:68
	ds_read2_b64 v[210:213], v167 offset0:72 offset1:76
	ds_read2_b64 v[214:217], v164 offset0:96 offset1:100
	ds_read2_b64 v[218:221], v164 offset0:104 offset1:108
	s_waitcnt lgkmcnt(8)
	v_mfma_f32_16x16x32_bf16 v[96:99], v[80:83], v[44:47], v[96:99]
	v_mfma_f32_16x16x32_bf16 v[80:83], v[80:83], v[32:35], v[88:91]
	s_nop 2
	v_max3_f32 v88, v68, s4, v69
	v_max3_f32 v89, v72, s4, v73
	v_max3_f32 v88, v88, v70, v71
	v_max3_f32 v89, v89, v74, v75
	v_max3_f32 v88, v88, v64, v65
	v_max3_f32 v89, v89, v100, v101
	v_max3_f32 v88, v88, v66, v67
	v_max3_f32 v89, v89, v102, v103
	v_max3_f32 v88, v88, v92, v93
	v_max3_f32 v89, v89, v76, v77
	v_max3_f32 v88, v88, v94, v95
	v_max3_f32 v89, v89, v78, v79
	v_max3_f32 v88, v88, v96, v97
	v_max3_f32 v89, v89, v80, v81
	v_max3_f32 v88, v88, v98, v99
	v_max3_f32 v89, v89, v82, v83
	v_mov_b32_e32 v90, v88
	v_mov_b32_e32 v91, v88
	v_mov_b32_e32 v164, v89
	v_mov_b32_e32 v166, v89
	v_permlane16_swap_b32_e32 v90, v91
	s_nop 0
	v_permlane16_swap_b32_e32 v164, v166
	v_cndmask_b32_e64 v90, v90, v91, s[10:11]
	v_cndmask_b32_e64 v91, v164, v166, s[10:11]
	v_max_f32_e32 v90, v90, v90
	v_max_f32_e32 v91, v91, v91
	v_max_f32_e32 v88, v88, v90
	v_max_f32_e32 v89, v89, v91
	v_mov_b32_e32 v90, v88
	v_mov_b32_e32 v91, v88
	v_mov_b32_e32 v164, v89
	v_mov_b32_e32 v166, v89
	v_permlane32_swap_b32_e32 v90, v91
	s_nop 0
	v_permlane32_swap_b32_e32 v164, v166
	v_cndmask_b32_e64 v90, v90, v91, s[12:13]
	v_cndmask_b32_e64 v91, v164, v166, s[12:13]
	v_max3_f32 v164, v163, v89, v91
	v_max3_f32 v166, v165, v88, v90
	v_sub_f32_e32 v89, v163, v164
	v_sub_f32_e32 v88, v165, v166
	v_sub_f32_e32 v68, v68, v166
	v_sub_f32_e32 v90, v72, v164
	v_sub_f32_e32 v69, v69, v166
	v_sub_f32_e32 v91, v73, v164
	v_sub_f32_e32 v70, v70, v166
	v_sub_f32_e32 v163, v74, v164
	v_sub_f32_e32 v71, v71, v166
	v_sub_f32_e32 v165, v75, v164
	v_sub_f32_e32 v64, v64, v166
	v_sub_f32_e32 v100, v100, v164
	v_sub_f32_e32 v65, v65, v166
	v_sub_f32_e32 v101, v101, v164
	v_sub_f32_e32 v66, v66, v166
	v_sub_f32_e32 v102, v102, v164
	v_sub_f32_e32 v67, v67, v166
	v_sub_f32_e32 v103, v103, v164
	v_exp_f32_e32 v73, v89
	v_sub_f32_e32 v167, v92, v166
	v_sub_f32_e32 v179, v76, v164
	v_sub_f32_e32 v178, v93, v166
	v_sub_f32_e32 v185, v77, v164
	v_sub_f32_e32 v187, v78, v164
	v_sub_f32_e32 v222, v79, v164
	v_sub_f32_e32 v224, v80, v164
	v_sub_f32_e32 v225, v81, v164
	v_sub_f32_e32 v227, v82, v164
	v_sub_f32_e32 v228, v83, v164
	v_exp_f32_e32 v72, v88
	v_exp_f32_e32 v74, v68
	v_exp_f32_e32 v75, v90
	v_exp_f32_e32 v76, v69
	v_exp_f32_e32 v77, v91
	v_exp_f32_e32 v78, v70
	v_exp_f32_e32 v79, v163
	v_exp_f32_e32 v80, v71
	v_exp_f32_e32 v81, v165
	v_exp_f32_e32 v82, v64
	v_exp_f32_e32 v83, v100
	v_exp_f32_e32 v88, v65
	v_exp_f32_e32 v89, v101
	v_exp_f32_e32 v90, v66
	v_exp_f32_e32 v91, v102
	v_exp_f32_e32 v92, v67
	v_exp_f32_e32 v93, v103
	v_sub_f32_e32 v186, v94, v166
	v_sub_f32_e32 v226, v98, v166
	v_exp_f32_e32 v98, v186
	v_mov_b32_e32 v186, v73
	v_sub_f32_e32 v95, v95, v166
	v_sub_f32_e32 v223, v96, v166
	v_sub_f32_e32 v97, v97, v166
	v_sub_f32_e32 v99, v99, v166
	v_pk_mul_f32 v[62:63], v[62:63], v[72:73] op_sel_hi:[1,0]
	v_pk_mul_f32 v[60:61], v[60:61], v[72:73] op_sel_hi:[1,0]
	v_pk_mul_f32 v[58:59], v[58:59], v[72:73] op_sel_hi:[1,0]
	v_cvt_pk_bf16_f32 v64, v74, v76
	v_cvt_pk_bf16_f32 v65, v78, v80
	v_cvt_pk_bf16_f32 v66, v82, v88
	v_cvt_pk_bf16_f32 v67, v90, v92
	v_pk_mul_f32 v[56:57], v[56:57], v[72:73] op_sel_hi:[1,0]
	v_cvt_pk_bf16_f32 v68, v75, v77
	v_cvt_pk_bf16_f32 v69, v79, v81
	v_cvt_pk_bf16_f32 v70, v83, v89
	v_cvt_pk_bf16_f32 v71, v91, v93
	v_pk_mul_f32 v[30:31], v[30:31], v[186:187] op_sel_hi:[1,0]
	v_pk_mul_f32 v[28:29], v[28:29], v[186:187] op_sel_hi:[1,0]
	v_pk_mul_f32 v[26:27], v[26:27], v[186:187] op_sel_hi:[1,0]
	v_pk_mul_f32 v[24:25], v[24:25], v[186:187] op_sel_hi:[1,0]
	v_exp_f32_e32 v94, v167
	v_exp_f32_e32 v96, v178
	v_exp_f32_e32 v100, v95
	v_exp_f32_e32 v102, v223
	v_exp_f32_e32 v178, v97
	s_waitcnt lgkmcnt(7)
	v_mfma_f32_16x16x32_bf16 v[60:63], v[104:107], v[64:67], v[60:63]
	v_mul_f32_e64 v54, v54, v72
	v_mul_f32_e64 v55, v55, v72
	v_pk_mul_f32 v[52:53], v[52:53], v[72:73] op_sel_hi:[1,0]
	v_pk_mul_f32 v[50:51], v[50:51], v[72:73] op_sel_hi:[1,0]
	s_waitcnt lgkmcnt(5)
	v_mfma_f32_16x16x32_bf16 v[56:59], v[84:87], v[64:67], v[56:59]
	v_mul_f32_e64 v48, v48, v72
	v_mul_f32_e64 v49, v49, v72
	v_exp_f32_e32 v95, v179
	v_exp_f32_e32 v97, v185
	v_mfma_f32_16x16x32_bf16 v[28:31], v[104:107], v[68:71], v[28:31]
	v_exp_f32_e32 v104, v226
	v_exp_f32_e32 v101, v222
	v_exp_f32_e32 v103, v224
	v_mfma_f32_16x16x32_bf16 v[24:27], v[84:87], v[68:71], v[24:27]
	v_exp_f32_e32 v84, v99
	v_exp_f32_e32 v99, v187
	v_exp_f32_e32 v179, v225
	s_waitcnt lgkmcnt(3)
	v_mfma_f32_16x16x32_bf16 v[52:55], v[206:209], v[64:67], v[52:55]
	v_exp_f32_e32 v105, v227
	v_pk_mul_f32 v[22:23], v[22:23], v[186:187] op_sel_hi:[1,0]
	v_pk_mul_f32 v[20:21], v[20:21], v[186:187] op_sel_hi:[1,0]
	s_waitcnt lgkmcnt(1)
	v_mfma_f32_16x16x32_bf16 v[48:51], v[214:217], v[64:67], v[48:51]
	v_cvt_pk_bf16_f32 v64, v94, v96
	v_cvt_pk_bf16_f32 v65, v98, v100
	v_cvt_pk_bf16_f32 v66, v102, v178
	v_cvt_pk_bf16_f32 v67, v104, v84
	v_pk_mul_f32 v[18:19], v[18:19], v[186:187] op_sel_hi:[1,0]
	v_pk_mul_f32 v[16:17], v[16:17], v[186:187] op_sel_hi:[1,0]
	v_mfma_f32_16x16x32_bf16 v[60:63], v[198:201], v[64:67], v[60:63]
	v_exp_f32_e32 v85, v228
	v_mfma_f32_16x16x32_bf16 v[56:59], v[202:205], v[64:67], v[56:59]
	v_mfma_f32_16x16x32_bf16 v[52:55], v[210:213], v[64:67], v[52:55]
	s_waitcnt lgkmcnt(0)
	v_mfma_f32_16x16x32_bf16 v[48:51], v[218:221], v[64:67], v[48:51]
	v_add_f32_e64 v64, v74, 0
	v_add_f32_e64 v65, v75, 0
	v_pk_add_f32 v[64:65], v[76:77], v[64:65]
	v_mfma_f32_16x16x32_bf16 v[20:23], v[206:209], v[68:71], v[20:23]
	v_add_f32_e64 v64, v78, v64
	v_add_f32_e64 v65, v79, v65
	v_pk_add_f32 v[64:65], v[80:81], v[64:65]
	v_mfma_f32_16x16x32_bf16 v[16:19], v[214:217], v[68:71], v[16:19]
	v_add_f32_e64 v64, v82, v64
	v_add_f32_e64 v65, v83, v65
	v_cvt_pk_bf16_f32 v68, v95, v97
	v_pk_add_f32 v[64:65], v[88:89], v[64:65]
	v_cvt_pk_bf16_f32 v69, v99, v101
	v_pk_add_f32 v[64:65], v[90:91], v[64:65]
	v_cvt_pk_bf16_f32 v70, v103, v179
	v_pk_add_f32 v[64:65], v[92:93], v[64:65]
	v_cvt_pk_bf16_f32 v71, v105, v85
	v_pk_add_f32 v[64:65], v[94:95], v[64:65]
	s_nop 0
	v_pk_add_f32 v[64:65], v[96:97], v[64:65]
	v_mfma_f32_16x16x32_bf16 v[28:31], v[198:201], v[68:71], v[28:31]
	v_add_f32_e64 v64, v98, v64
	v_add_f32_e64 v65, v99, v65
	v_pk_add_f32 v[64:65], v[100:101], v[64:65]
	v_mfma_f32_16x16x32_bf16 v[24:27], v[202:205], v[68:71], v[24:27]
	v_add_f32_e64 v64, v102, v64
	v_add_f32_e64 v65, v103, v65
	v_pk_add_f32 v[64:65], v[178:179], v[64:65]
	v_mfma_f32_16x16x32_bf16 v[20:23], v[210:213], v[68:71], v[20:23]
	v_add_f32_e64 v64, v104, v64
	v_add_f32_e64 v65, v105, v65
	v_pk_add_f32 v[64:65], v[84:85], v[64:65]
	v_mfma_f32_16x16x32_bf16 v[16:19], v[218:221], v[68:71], v[16:19]
	v_mov_b32_e32 v66, v64
	v_mov_b32_e32 v68, v64
	v_mov_b32_e32 v67, v65
	v_mov_b32_e32 v69, v65
	v_permlane16_swap_b32_e32 v66, v68
	s_nop 0
	v_permlane16_swap_b32_e32 v67, v69
	v_cndmask_b32_e64 v67, v67, v69, s[10:11]
	v_cndmask_b32_e64 v66, v66, v68, s[10:11]
	v_pk_add_f32 v[64:65], v[64:65], v[66:67]
	s_nop 0
	v_mov_b32_e32 v66, v64
	v_mov_b32_e32 v68, v64
	v_mov_b32_e32 v67, v65
	v_mov_b32_e32 v69, v65
	v_permlane32_swap_b32_e32 v66, v68
	s_nop 0
	v_permlane32_swap_b32_e32 v67, v69
	v_cndmask_b32_e64 v67, v67, v69, s[12:13]
	v_cndmask_b32_e64 v66, v66, v68, s[12:13]
	v_pk_add_f32 v[64:65], v[64:65], v[66:67]
	s_nop 0
	v_pk_fma_f32 v[158:159], v[158:159], v[72:73], v[64:65]
	s_cmpk_lg_i32 s0, 0x80
	s_cbranch_scc1 .Lpast_qskip
	v_mov_b32_e32 v233, 0
	s_waitcnt vmcnt(1)
	v_and_b32_e32 v137, 0xfff, v141
	v_lshlrev_b32_e32 v232, 7, v137
	v_lshl_add_u64 v[4:5], v[156:157], 0, v[232:233]
	global_load_dwordx4 v[0:3], v[4:5], off
	s_nop 0
	global_load_dwordx4 v[4:7], v[4:5], off offset:64
	s_waitcnt vmcnt(2)
	v_and_b32_e32 v139, 0xfff, v149
	v_lshlrev_b32_e32 v232, 7, v139
	v_lshl_add_u64 v[12:13], v[156:157], 0, v[232:233]
	global_load_dwordx4 v[8:11], v[12:13], off
	s_nop 0
	global_load_dwordx4 v[12:15], v[12:13], off offset:64
.Lpast_qskip:
	s_cmpk_eq_i32 s0, 0x200
	s_cbranch_scc0 .LBB0_259
	s_and_saveexec_b64 s[30:31], s[28:29]
	s_cbranch_execz .LBB0_263
	v_ashrrev_i32_e32 v163, 31, v162
	v_rcp_f32_e32 v36, v158
	v_lshrrev_b32_e32 v116, 12, v161
	v_lshl_add_u64 v[34:35], s[14:15], 0, v[162:163]
	v_mad_u64_u32 v[32:33], s[28:29], v34, 3, v[116:117]
	v_mad_i32_i24 v33, v35, 3, v33
	v_lshlrev_b64 v[34:35], 7, v[32:33]
	v_pk_mul_f32 v[38:39], v[60:61], v[36:37] op_sel_hi:[1,0]
	v_pk_mul_f32 v[40:41], v[62:63], v[36:37] op_sel_hi:[1,0]
	v_cvt_pk_bf16_f32 v38, v38, v39
	v_cvt_pk_bf16_f32 v39, v40, v41
	v_lshl_add_u64 v[34:35], v[130:131], 0, v[34:35]
	global_store_dwordx2 v[34:35], v[38:39], off
	v_pk_mul_f32 v[38:39], v[36:37], v[56:57] op_sel_hi:[0,1]
	v_pk_mul_f32 v[40:41], v[36:37], v[58:59] op_sel_hi:[0,1]
	v_cvt_pk_bf16_f32 v38, v38, v39
	v_cvt_pk_bf16_f32 v39, v40, v41
	global_store_dwordx2 v[34:35], v[38:39], off offset:32
	v_pk_mul_f32 v[38:39], v[36:37], v[52:53] op_sel_hi:[0,1]
	v_pk_mul_f32 v[40:41], v[36:37], v[54:55] op_sel_hi:[0,1]
	v_cvt_pk_bf16_f32 v38, v38, v39
	v_cvt_pk_bf16_f32 v39, v40, v41
	global_store_dwordx2 v[34:35], v[38:39], off offset:64
	v_pk_mul_f32 v[38:39], v[36:37], v[48:49] op_sel_hi:[0,1]
	v_pk_mul_f32 v[36:37], v[36:37], v[50:51] op_sel_hi:[0,1]
	v_cvt_pk_bf16_f32 v38, v38, v39
	v_cvt_pk_bf16_f32 v39, v36, v37
	global_store_dwordx2 v[34:35], v[38:39], off offset:96
	s_and_b64 exec, exec, s[8:9]
	s_cbranch_execz .LBB0_263
	v_lshl_add_u64 v[32:33], v[32:33], 3, s[42:43]
	v_mov_b32_e32 v167, v158
	global_store_dwordx2 v[32:33], v[166:167], off sc1
